# kv up-projection tile map: every XCD takes its own 12 row tiles plus 2 of the 16 cache row tiles (was: XCD 7 had all cache tiles)
# speedup vs baseline: 1.0099x; 1.0034x over previous
.LBB0_497:
	s_lshr_b32 s2, s1, 3
	s_and_b32 s6, s2, 14
	v_readlane_b32 s2, v246, 16
	s_and_b32 s9, s82, 7
	s_add_i32 s2, s6, s2
	s_lshl_b32 s9, s9, 1
	s_add_i32 s9, s9, s6
	s_addk_i32 s9, 0x54
	s_cmpk_lt_u32 s6, 12
	s_cselect_b32 s6, s2, s9
	s_and_b32 s2, s1, 1
	s_or_b32 s2, s6, s2
	s_bfe_u32 s18, s1, 0x30001
	s_lshl_b32 s8, s2, 7
	s_cmpk_gt_u32 s6, 0x5f
	s_mov_b64 s[10:11], -1
	s_cbranch_scc0 .LBB0_819
	s_add_i32 s9, s8, 0xffffd000
	s_load_dwordx2 s[10:11], s[54:55], 0x10
	s_lshr_b32 s9, s9, 8
	s_and_b32 s9, s9, 0xfffffe
	s_add_i32 s12, s9, s0
	s_ashr_i32 s13, s12, 31
	s_lshl_b64 s[12:13], s[12:13], 19
	s_waitcnt lgkmcnt(0)
	s_add_u32 s9, s10, s12
	s_addc_u32 s10, s11, s13
	s_lshl_b32 s2, s2, 17
	s_waitcnt vmcnt(33)
	v_mov_b32 v171, v194
	s_and_b32 s2, s2, 0x60000
	v_ashrrev_i32_e32 v78, 3, v171
	s_waitcnt vmcnt(0)
	v_lshl_add_u32 v2, s18, 7, v78
	s_add_u32 s2, s9, s2
	v_ashrrev_i32_e32 v3, 31, v2
	s_addc_u32 s9, s10, 0
	s_lshl_b32 s10, s8, 10
	v_lshlrev_b64 v[2:3], 9, v[2:3]
	v_lshlrev_b32_e32 v0, 4, v171
	s_sub_u32 s10, 0, s10
	v_lshl_add_u64 v[2:3], s[56:57], 0, v[2:3]
	v_and_b32_e32 v0, 0x70, v0
	v_ashrrev_i32_e32 v79, 4, v171
	s_subb_u32 s11, 0, 0
	v_lshl_add_u64 v[98:99], v[2:3], 0, v[0:1]
	v_add_u32_e32 v2, s8, v79
	s_add_u32 s10, s2, s10
	v_ashrrev_i32_e32 v3, 31, v2
	v_lshlrev_b32_e32 v4, 2, v171
	s_addc_u32 s11, s9, s11
	v_lshlrev_b64 v[2:3], 10, v[2:3]
	v_and_b32_e32 v80, 60, v4
	v_lshl_add_u64 v[2:3], s[10:11], 0, v[2:3]
	v_lshlrev_b32_e32 v4, 2, v80
	v_mov_b32_e32 v5, v1
	v_lshl_add_u64 v[66:67], v[2:3], 0, v[4:5]
	s_movk_i32 s11, 0x4000
	v_add_co_u32_e32 v68, vcc, s11, v66
	s_mov_b32 s10, 0x8000
	s_nop 0
	v_addc_co_u32_e32 v69, vcc, 0, v67, vcc
	v_add_co_u32_e32 v70, vcc, s10, v66
	s_mov_b32 s9, 0xc000
	s_nop 0
	v_addc_co_u32_e32 v71, vcc, 0, v67, vcc
	v_add_co_u32_e32 v72, vcc, s9, v66
	s_mov_b32 s2, 0x10000
	s_nop 0
	v_addc_co_u32_e32 v73, vcc, 0, v67, vcc
	s_barrier
	s_barrier
	global_load_dwordx4 v[2:5], v[66:67], off
	global_load_dwordx4 v[6:9], v[68:69], off
	v_add_co_u32_e32 v74, vcc, s2, v66
	s_mov_b32 s2, 0x14000
	s_nop 0
	v_addc_co_u32_e32 v75, vcc, 0, v67, vcc
	v_add_co_u32_e32 v76, vcc, s2, v66
	global_load_dwordx4 v[10:13], v[70:71], off
	global_load_dwordx4 v[14:17], v[72:73], off
	v_addc_co_u32_e32 v77, vcc, 0, v67, vcc
	s_mov_b32 s2, 0x18000
	v_add_co_u32_e32 v100, vcc, s2, v66
	global_load_dwordx4 v[18:21], v[74:75], off
	global_load_dwordx4 v[22:25], v[76:77], off
	v_addc_co_u32_e32 v101, vcc, 0, v67, vcc
	s_mov_b32 s2, 0x1c000
	v_add_co_u32_e32 v102, vcc, s2, v66
	global_load_dwordx4 v[26:29], v[100:101], off
	s_nop 0
	v_addc_co_u32_e32 v103, vcc, 0, v67, vcc
	v_add_co_u32_e32 v104, vcc, s11, v98
	global_load_dwordx4 v[30:33], v[102:103], off
	global_load_dwordx4 v[34:37], v[98:99], off
	v_addc_co_u32_e32 v105, vcc, 0, v99, vcc
	v_add_co_u32_e32 v106, vcc, s10, v98
	global_load_dwordx4 v[38:41], v[104:105], off
	s_nop 0
	v_addc_co_u32_e32 v107, vcc, 0, v99, vcc
	global_load_dwordx4 v[42:45], v[106:107], off
	v_add_co_u32_e32 v110, vcc, s9, v98
	s_mov_b32 s2, 0xfffffc0
	s_nop 0
	v_addc_co_u32_e32 v111, vcc, 0, v99, vcc
	global_load_dwordx4 v[46:49], v[110:111], off
	global_load_dwordx4 v[50:53], v[66:67], off offset:256
	global_load_dwordx4 v[54:57], v[68:69], off offset:256
	global_load_dwordx4 v[58:61], v[70:71], off offset:256
	global_load_dwordx4 v[62:65], v[72:73], off offset:256
	global_load_dwordx4 v[114:117], v[74:75], off offset:256
	global_load_dwordx4 v[118:121], v[76:77], off offset:256
	global_load_dwordx4 v[122:125], v[100:101], off offset:256
	global_load_dwordx4 v[126:129], v[102:103], off offset:256
	global_load_dwordx4 v[130:133], v[98:99], off offset:128
	global_load_dwordx4 v[134:137], v[104:105], off offset:128
	global_load_dwordx4 v[138:141], v[110:111], off offset:128
	s_waitcnt vmcnt(22)
	v_cvt_pk_bf16_f32 v2, v2, v3
	v_cvt_pk_bf16_f32 v3, v4, v5
	v_mul_lo_u32 v4, v79, s34
	v_lshlrev_b32_e32 v5, 1, v80
	v_add3_u32 v192, 16, v4, v5
	ds_write_b64 v192, v[2:3]
	s_waitcnt vmcnt(21)
	v_cvt_pk_bf16_f32 v2, v6, v7
	v_cvt_pk_bf16_f32 v3, v8, v9
	ds_write_b64 v192, v[2:3] offset:2304
	s_waitcnt vmcnt(20)
	v_cvt_pk_bf16_f32 v2, v10, v11
	v_cvt_pk_bf16_f32 v3, v12, v13
	ds_write_b64 v192, v[2:3] offset:4608
	s_waitcnt vmcnt(19)
	v_cvt_pk_bf16_f32 v2, v14, v15
	v_cvt_pk_bf16_f32 v3, v16, v17
	ds_write_b64 v192, v[2:3] offset:6912
	v_and_b32_e32 v6, 31, v171
	s_waitcnt vmcnt(18)
	v_cvt_pk_bf16_f32 v2, v18, v19
	v_cvt_pk_bf16_f32 v3, v20, v21
	ds_write_b64 v192, v[2:3] offset:9216
	s_waitcnt vmcnt(17)
	v_cvt_pk_bf16_f32 v2, v22, v23
	v_cvt_pk_bf16_f32 v3, v24, v25
	ds_write_b64 v192, v[2:3] offset:11520
	v_lshrrev_b32_e32 v8, 1, v171
	s_waitcnt vmcnt(16)
	v_cvt_pk_bf16_f32 v2, v26, v27
	v_cvt_pk_bf16_f32 v3, v28, v29
	ds_write_b64 v192, v[2:3] offset:13824
	v_and_or_b32 v9, v8, s2, v6
	s_waitcnt vmcnt(15)
	v_cvt_pk_bf16_f32 v2, v30, v31
	v_cvt_pk_bf16_f32 v3, v32, v33
	ds_write_b64 v192, v[2:3] offset:16128
	v_mul_lo_u32 v2, v78, s34
	v_add3_u32 v0, 16, v2, v0
	s_waitcnt vmcnt(14)
	ds_write_b128 v0, v[34:37] offset:18432
	s_waitcnt vmcnt(13)
	ds_write_b128 v0, v[38:41] offset:23040
	global_load_dwordx4 v[142:145], v[104:105], off offset:256
	s_waitcnt vmcnt(13)
	ds_write_b128 v0, v[42:45] offset:27648
	s_waitcnt vmcnt(12)
	ds_write_b128 v0, v[46:49] offset:32256
	global_load_dwordx4 v[146:149], v[98:99], off offset:256
	global_load_dwordx4 v[2:5], v[106:107], off offset:128
	global_load_dwordx4 v[150:153], v[106:107], off offset:256
	global_load_dwordx4 v[154:157], v[110:111], off offset:256
	global_load_dwordx4 v[158:161], v[66:67], off offset:512
	global_load_dwordx4 v[94:97], v[66:67], off offset:768
	global_load_dwordx4 v[162:165], v[68:69], off offset:512
	global_load_dwordx4 v[90:93], v[68:69], off offset:768
	global_load_dwordx4 v[166:169], v[70:71], off offset:512
	global_load_dwordx4 v[86:89], v[70:71], off offset:768
	global_load_dwordx4 v[172:175], v[72:73], off offset:512
	global_load_dwordx4 v[82:85], v[72:73], off offset:768
	global_load_dwordx4 v[176:179], v[74:75], off offset:512
	global_load_dwordx4 v[78:81], v[74:75], off offset:768
	global_load_dwordx4 v[180:183], v[76:77], off offset:512
	s_nop 0
	global_load_dwordx4 v[74:77], v[76:77], off offset:768
	s_nop 0
	global_load_dwordx4 v[184:187], v[100:101], off offset:512
	global_load_dwordx4 v[70:73], v[100:101], off offset:768
	global_load_dwordx4 v[188:191], v[102:103], off offset:512
	global_load_dwordx4 v[66:69], v[102:103], off offset:768
	s_waitcnt lgkmcnt(0)
	s_barrier
	global_load_dwordx4 v[98:101], v[98:99], off offset:384
	s_nop 0
	global_load_dwordx4 v[102:105], v[104:105], off offset:384
	s_nop 0
	global_load_dwordx4 v[106:109], v[106:107], off offset:384
	s_nop 0
	global_load_dwordx4 v[110:113], v[110:111], off offset:384
	v_and_b32_e32 v6, 0x5f, v171
	v_mul_u32_u24_e32 v10, 0x48, v6
	s_waitcnt vmcnt(35)
	v_cvt_pk_bf16_f32 v6, v50, v51
	v_cvt_pk_bf16_f32 v7, v52, v53
	ds_write_b64 v192, v[6:7] offset:36864
	s_waitcnt vmcnt(34)
	v_cvt_pk_bf16_f32 v6, v54, v55
	v_cvt_pk_bf16_f32 v7, v56, v57
	ds_write_b64 v192, v[6:7] offset:39168
	s_waitcnt vmcnt(33)
	v_cvt_pk_bf16_f32 v6, v58, v59
	v_cvt_pk_bf16_f32 v7, v60, v61
	ds_write_b64 v192, v[6:7] offset:41472
	s_waitcnt vmcnt(32)
	v_cvt_pk_bf16_f32 v6, v62, v63
	v_cvt_pk_bf16_f32 v7, v64, v65
	ds_write_b64 v192, v[6:7] offset:43776
	s_waitcnt vmcnt(31)
	v_cvt_pk_bf16_f32 v6, v114, v115
	v_cvt_pk_bf16_f32 v7, v116, v117
	ds_write_b64 v192, v[6:7] offset:46080
	s_waitcnt vmcnt(30)
	v_cvt_pk_bf16_f32 v6, v118, v119
	v_cvt_pk_bf16_f32 v7, v120, v121
	ds_write_b64 v192, v[6:7] offset:48384
	s_waitcnt vmcnt(29)
	v_cvt_pk_bf16_f32 v6, v122, v123
	v_cvt_pk_bf16_f32 v7, v124, v125
	ds_write_b64 v192, v[6:7] offset:50688
	s_waitcnt vmcnt(28)
	v_cvt_pk_bf16_f32 v6, v126, v127
	v_cvt_pk_bf16_f32 v7, v128, v129
	ds_write_b64 v192, v[6:7] offset:52992
	v_add_u32_e32 v171, 0xd800, v0
	s_waitcnt vmcnt(27)
	ds_write_b128 v0, v[130:133] offset:55296
	s_waitcnt vmcnt(26)
	ds_write_b128 v0, v[134:137] offset:59904
	s_waitcnt vmcnt(22)
	ds_write_b128 v0, v[2:5] offset:64512
	ds_write_b128 v171, v[138:141] offset:13824
	s_setprio 2
	v_mul_lo_u32 v2, v9, s34
	v_and_b32_e32 v3, 16, v8
	v_add3_u32 v193, 16, v2, v3
	v_lshlrev_b32_e32 v2, 1, v10
	v_add3_u32 v211, 16, v2, v3
	ds_read_b128 v[2:5], v193
	ds_read_b128 v[114:117], v193 offset:32
	ds_read_b128 v[6:9], v193 offset:4608
	ds_read_b128 v[118:121], v193 offset:4640
	ds_read_b128 v[10:13], v211 offset:18432
	ds_read_b128 v[122:125], v211 offset:18464
	ds_read_b128 v[14:17], v211 offset:23040
	ds_read_b128 v[126:129], v211 offset:23072
	s_waitcnt lgkmcnt(3)
	v_mfma_f32_32x32x16_bf16 v[50:65], v[2:5], v[10:13], 0
	s_waitcnt lgkmcnt(1)
	v_mfma_f32_32x32x16_bf16 v[34:49], v[2:5], v[14:17], 0
	v_mfma_f32_32x32x16_bf16 v[18:33], v[6:9], v[10:13], 0
	v_mfma_f32_32x32x16_bf16 v[2:17], v[6:9], v[14:17], 0
	ds_read_b128 v[130:133], v193 offset:64
	ds_read_b128 v[134:137], v193 offset:4672
	ds_read_b128 v[138:141], v211 offset:18496
	ds_read_b128 v[212:215], v211 offset:23104
	v_mfma_f32_32x32x16_bf16 v[50:65], v[114:117], v[122:125], v[50:65]
	s_waitcnt lgkmcnt(4)
	v_mfma_f32_32x32x16_bf16 v[34:49], v[114:117], v[126:129], v[34:49]
	v_mfma_f32_32x32x16_bf16 v[18:33], v[118:121], v[122:125], v[18:33]
	v_mfma_f32_32x32x16_bf16 v[2:17], v[118:121], v[126:129], v[2:17]
	ds_read_b128 v[114:117], v193 offset:96
	ds_read_b128 v[118:121], v193 offset:4704
	ds_read_b128 v[122:125], v211 offset:18528
	ds_read_b128 v[126:129], v211 offset:23136
	s_waitcnt lgkmcnt(5)
	v_mfma_f32_32x32x16_bf16 v[50:65], v[130:133], v[138:141], v[50:65]
	s_waitcnt lgkmcnt(4)
	v_mfma_f32_32x32x16_bf16 v[34:49], v[130:133], v[212:215], v[34:49]
	v_mfma_f32_32x32x16_bf16 v[18:33], v[134:137], v[138:141], v[18:33]
	v_mfma_f32_32x32x16_bf16 v[2:17], v[134:137], v[212:215], v[2:17]
	s_waitcnt lgkmcnt(1)
	v_mfma_f32_32x32x16_bf16 v[50:65], v[114:117], v[122:125], v[50:65]
	s_waitcnt lgkmcnt(0)
	v_mfma_f32_32x32x16_bf16 v[34:49], v[114:117], v[126:129], v[34:49]
	v_mfma_f32_32x32x16_bf16 v[18:33], v[118:121], v[122:125], v[18:33]
	v_mfma_f32_32x32x16_bf16 v[2:17], v[118:121], v[126:129], v[2:17]
	s_setprio 0
	s_waitcnt vmcnt(19)
	v_cvt_pk_bf16_f32 v114, v158, v159
	v_cvt_pk_bf16_f32 v115, v160, v161
	s_barrier
	ds_write_b64 v192, v[114:115]
	s_waitcnt vmcnt(17)
	v_cvt_pk_bf16_f32 v114, v162, v163
	v_cvt_pk_bf16_f32 v115, v164, v165
	ds_write_b64 v192, v[114:115] offset:2304
	s_waitcnt vmcnt(15)
	v_cvt_pk_bf16_f32 v114, v166, v167
	v_cvt_pk_bf16_f32 v115, v168, v169
	ds_write_b64 v192, v[114:115] offset:4608
	s_waitcnt vmcnt(13)
	v_cvt_pk_bf16_f32 v114, v172, v173
	v_cvt_pk_bf16_f32 v115, v174, v175
	ds_write_b64 v192, v[114:115] offset:6912
	s_waitcnt vmcnt(11)
	v_cvt_pk_bf16_f32 v114, v176, v177
	v_cvt_pk_bf16_f32 v115, v178, v179
	ds_write_b64 v192, v[114:115] offset:9216
	s_waitcnt vmcnt(9)
	v_cvt_pk_bf16_f32 v114, v180, v181
	v_cvt_pk_bf16_f32 v115, v182, v183
	ds_write_b64 v192, v[114:115] offset:11520
	s_waitcnt vmcnt(7)
	v_cvt_pk_bf16_f32 v114, v184, v185
	v_cvt_pk_bf16_f32 v115, v186, v187
	ds_write_b64 v192, v[114:115] offset:13824
	s_waitcnt vmcnt(5)
	v_cvt_pk_bf16_f32 v114, v188, v189
	v_cvt_pk_bf16_f32 v115, v190, v191
	ds_write_b64 v192, v[114:115] offset:16128
	ds_write_b128 v0, v[146:149] offset:18432
	ds_write_b128 v0, v[142:145] offset:23040
	ds_write_b128 v0, v[150:153] offset:27648
	ds_write_b128 v0, v[154:157] offset:32256
	s_setprio 2
	ds_read_b128 v[114:117], v193 offset:36864
	ds_read_b128 v[118:121], v193 offset:36896
	ds_read_b128 v[122:125], v193 offset:41472
	ds_read_b128 v[126:129], v193 offset:41504
	ds_read_b128 v[130:133], v211 offset:55296
	ds_read_b128 v[134:137], v211 offset:55328
	ds_read_b128 v[138:141], v211 offset:59904
	ds_read_b128 v[142:145], v211 offset:59936
	s_waitcnt lgkmcnt(3)
	v_mfma_f32_32x32x16_bf16 v[50:65], v[114:117], v[130:133], v[50:65]
	s_waitcnt lgkmcnt(1)
	v_mfma_f32_32x32x16_bf16 v[34:49], v[114:117], v[138:141], v[34:49]
	v_mfma_f32_32x32x16_bf16 v[18:33], v[122:125], v[130:133], v[18:33]
	v_mfma_f32_32x32x16_bf16 v[2:17], v[122:125], v[138:141], v[2:17]
	ds_read_b128 v[114:117], v193 offset:36928
	ds_read_b128 v[122:125], v193 offset:41536
	ds_read_b128 v[130:133], v211 offset:55360
	ds_read_b128 v[138:141], v211 offset:59968
	v_mfma_f32_32x32x16_bf16 v[50:65], v[118:121], v[134:137], v[50:65]
	s_waitcnt lgkmcnt(4)
	v_mfma_f32_32x32x16_bf16 v[34:49], v[118:121], v[142:145], v[34:49]
	v_mfma_f32_32x32x16_bf16 v[18:33], v[126:129], v[134:137], v[18:33]
	v_mfma_f32_32x32x16_bf16 v[2:17], v[126:129], v[142:145], v[2:17]
	ds_read_b128 v[118:121], v193 offset:36960
	ds_read_b128 v[126:129], v193 offset:41568
	ds_read_b128 v[134:137], v211 offset:55392
	ds_read_b128 v[142:145], v211 offset:60000
	s_waitcnt lgkmcnt(5)
	v_mfma_f32_32x32x16_bf16 v[50:65], v[114:117], v[130:133], v[50:65]
	s_waitcnt lgkmcnt(4)
	v_mfma_f32_32x32x16_bf16 v[34:49], v[114:117], v[138:141], v[34:49]
	v_mfma_f32_32x32x16_bf16 v[18:33], v[122:125], v[130:133], v[18:33]
	v_mfma_f32_32x32x16_bf16 v[2:17], v[122:125], v[138:141], v[2:17]
	s_waitcnt lgkmcnt(1)
	v_mfma_f32_32x32x16_bf16 v[50:65], v[118:121], v[134:137], v[50:65]
	s_waitcnt lgkmcnt(0)
	v_mfma_f32_32x32x16_bf16 v[34:49], v[118:121], v[142:145], v[34:49]
	v_mfma_f32_32x32x16_bf16 v[18:33], v[126:129], v[134:137], v[18:33]
	v_mfma_f32_32x32x16_bf16 v[2:17], v[126:129], v[142:145], v[2:17]
	s_setprio 0
	v_cvt_pk_bf16_f32 v94, v94, v95
	v_cvt_pk_bf16_f32 v95, v96, v97
	v_cvt_pk_bf16_f32 v90, v90, v91
	v_cvt_pk_bf16_f32 v91, v92, v93
	v_cvt_pk_bf16_f32 v86, v86, v87
	v_cvt_pk_bf16_f32 v87, v88, v89
	v_cvt_pk_bf16_f32 v82, v82, v83
	v_cvt_pk_bf16_f32 v83, v84, v85
	v_cvt_pk_bf16_f32 v78, v78, v79
	v_cvt_pk_bf16_f32 v79, v80, v81
	v_cvt_pk_bf16_f32 v74, v74, v75
	v_cvt_pk_bf16_f32 v75, v76, v77
	v_cvt_pk_bf16_f32 v70, v70, v71
	v_cvt_pk_bf16_f32 v71, v72, v73
	s_waitcnt vmcnt(4)
	v_cvt_pk_bf16_f32 v66, v66, v67
	v_cvt_pk_bf16_f32 v67, v68, v69
	s_barrier
	ds_write_b64 v192, v[94:95] offset:36864
	ds_write_b64 v192, v[90:91] offset:39168
	ds_write_b64 v192, v[86:87] offset:41472
	ds_write_b64 v192, v[82:83] offset:43776
	ds_write_b64 v192, v[78:79] offset:46080
	ds_write_b64 v192, v[74:75] offset:48384
	ds_write_b64 v192, v[70:71] offset:50688
	ds_write_b64 v192, v[66:67] offset:52992
	s_waitcnt vmcnt(3)
	ds_write_b128 v0, v[98:101] offset:55296
	s_waitcnt vmcnt(2)
	ds_write_b128 v0, v[102:105] offset:59904
	s_waitcnt vmcnt(1)
	ds_write_b128 v0, v[106:109] offset:64512
	s_waitcnt vmcnt(0)
	ds_write_b128 v171, v[110:113] offset:13824
	s_setprio 2
	ds_read_b128 v[66:69], v193
	ds_read_b128 v[70:73], v193 offset:32
	ds_read_b128 v[74:77], v193 offset:4608
	ds_read_b128 v[78:81], v193 offset:4640
	ds_read_b128 v[82:85], v211 offset:18432
	ds_read_b128 v[86:89], v211 offset:18464
	ds_read_b128 v[90:93], v211 offset:23040
	ds_read_b128 v[94:97], v211 offset:23072
	s_waitcnt lgkmcnt(3)
	v_mfma_f32_32x32x16_bf16 v[50:65], v[66:69], v[82:85], v[50:65]
	s_waitcnt lgkmcnt(1)
	v_mfma_f32_32x32x16_bf16 v[34:49], v[66:69], v[90:93], v[34:49]
	v_mfma_f32_32x32x16_bf16 v[18:33], v[74:77], v[82:85], v[18:33]
	v_mfma_f32_32x32x16_bf16 v[2:17], v[74:77], v[90:93], v[2:17]
	ds_read_b128 v[66:69], v193 offset:64
	ds_read_b128 v[74:77], v193 offset:4672
	ds_read_b128 v[82:85], v211 offset:18496
	ds_read_b128 v[90:93], v211 offset:23104
	v_mfma_f32_32x32x16_bf16 v[50:65], v[70:73], v[86:89], v[50:65]
	s_waitcnt lgkmcnt(4)
	v_mfma_f32_32x32x16_bf16 v[34:49], v[70:73], v[94:97], v[34:49]
	v_mfma_f32_32x32x16_bf16 v[18:33], v[78:81], v[86:89], v[18:33]
	v_mfma_f32_32x32x16_bf16 v[2:17], v[78:81], v[94:97], v[2:17]
	ds_read_b128 v[70:73], v193 offset:96
	ds_read_b128 v[78:81], v193 offset:4704
	ds_read_b128 v[86:89], v211 offset:18528
	ds_read_b128 v[94:97], v211 offset:23136
	s_waitcnt lgkmcnt(5)
	v_mfma_f32_32x32x16_bf16 v[50:65], v[66:69], v[82:85], v[50:65]
	s_waitcnt lgkmcnt(4)
	v_mfma_f32_32x32x16_bf16 v[34:49], v[66:69], v[90:93], v[34:49]
	v_mfma_f32_32x32x16_bf16 v[18:33], v[74:77], v[82:85], v[18:33]
	v_mfma_f32_32x32x16_bf16 v[2:17], v[74:77], v[90:93], v[2:17]
	s_waitcnt lgkmcnt(1)
	v_mfma_f32_32x32x16_bf16 v[50:65], v[70:73], v[86:89], v[50:65]
	s_waitcnt lgkmcnt(0)
	v_mfma_f32_32x32x16_bf16 v[34:49], v[70:73], v[94:97], v[34:49]
	v_mfma_f32_32x32x16_bf16 v[18:33], v[78:81], v[86:89], v[18:33]
	v_mfma_f32_32x32x16_bf16 v[2:17], v[78:81], v[94:97], v[2:17]
	s_setprio 0
	s_barrier
	s_setprio 2
	ds_read_b128 v[66:69], v193 offset:36864
	ds_read_b128 v[70:73], v193 offset:36896
	ds_read_b128 v[74:77], v193 offset:41472
	ds_read_b128 v[78:81], v193 offset:41504
	ds_read_b128 v[82:85], v211 offset:55296
	ds_read_b128 v[86:89], v211 offset:55328
	ds_read_b128 v[90:93], v211 offset:59904
	ds_read_b128 v[94:97], v211 offset:59936
	s_waitcnt lgkmcnt(3)
	v_mfma_f32_32x32x16_bf16 v[50:65], v[66:69], v[82:85], v[50:65]
	s_waitcnt lgkmcnt(1)
	v_mfma_f32_32x32x16_bf16 v[34:49], v[66:69], v[90:93], v[34:49]
	v_mfma_f32_32x32x16_bf16 v[18:33], v[74:77], v[82:85], v[18:33]
	v_mfma_f32_32x32x16_bf16 v[2:17], v[74:77], v[90:93], v[2:17]
	ds_read_b128 v[66:69], v193 offset:36928
	ds_read_b128 v[74:77], v193 offset:41536
	ds_read_b128 v[82:85], v211 offset:55360
	ds_read_b128 v[90:93], v211 offset:59968
	v_mfma_f32_32x32x16_bf16 v[50:65], v[70:73], v[86:89], v[50:65]
	s_waitcnt lgkmcnt(4)
	v_mfma_f32_32x32x16_bf16 v[34:49], v[70:73], v[94:97], v[34:49]
	v_mfma_f32_32x32x16_bf16 v[18:33], v[78:81], v[86:89], v[18:33]
	v_mfma_f32_32x32x16_bf16 v[2:17], v[78:81], v[94:97], v[2:17]
	ds_read_b128 v[70:73], v193 offset:36960
	ds_read_b128 v[78:81], v193 offset:41568
	ds_read_b128 v[86:89], v211 offset:55392
	ds_read_b128 v[94:97], v211 offset:60000
	s_waitcnt lgkmcnt(5)
	v_mfma_f32_32x32x16_bf16 v[50:65], v[66:69], v[82:85], v[50:65]
	s_waitcnt lgkmcnt(4)
	v_mfma_f32_32x32x16_bf16 v[34:49], v[66:69], v[90:93], v[34:49]
	v_mfma_f32_32x32x16_bf16 v[18:33], v[74:77], v[82:85], v[18:33]
	v_mfma_f32_32x32x16_bf16 v[2:17], v[74:77], v[90:93], v[2:17]
	s_waitcnt lgkmcnt(1)
	v_mfma_f32_32x32x16_bf16 v[50:65], v[70:73], v[86:89], v[50:65]
	s_waitcnt lgkmcnt(0)
	v_mfma_f32_32x32x16_bf16 v[34:49], v[70:73], v[94:97], v[34:49]
	v_mfma_f32_32x32x16_bf16 v[18:33], v[78:81], v[86:89], v[18:33]
	v_mfma_f32_32x32x16_bf16 v[2:17], v[78:81], v[94:97], v[2:17]
	s_setprio 0
	s_barrier
	v_mov_b32 v0, v194
	s_nop 0
	v_ashrrev_i32_e32 v66, 1, v0
	v_and_b32_e32 v66, 0xffffffc0, v66
	v_add_u32_e32 v78, s8, v66
	v_lshrrev_b32_e32 v66, 3, v0
	v_and_or_b32 v79, v66, 4, v78
	v_cmp_lt_i32_e64 s[40:41], s93, v79
	s_and_saveexec_b64 s[10:11], s[40:41]
	s_xor_b64 s[10:11], exec, s[10:11]
	s_cbranch_execz .LBB0_504
	v_cmp_lt_u32_e32 vcc, s92, v78
	s_and_saveexec_b64 s[12:13], vcc
	s_xor_b64 s[12:13], exec, s[12:13]
	v_add_u32_e32 v66, 0xffffd000, v78
	v_lshrrev_b32_e32 v69, 9, v66
	v_and_b32_e32 v70, 0x1c4, v79
	s_andn2_saveexec_b64 s[12:13], s[12:13]
	v_add_u32_e32 v66, 0xfffff000, v78
	v_lshrrev_b32_e32 v69, 11, v66
	v_and_b32_e32 v66, 0x7c4, v79
	v_add_u32_e32 v70, 0x200, v66
	s_or_b64 exec, exec, s[12:13]
